# route_unit: ballot/mbcnt parallel slot ranking over 256 threads replaces the 32-thread serial LDS scan
# speedup vs baseline: 1.0324x; 1.0086x over previous
.LBB0_1486:
	s_or_b64 exec, exec, s[10:11]
	s_waitcnt lgkmcnt(0)
	s_barrier
	s_and_saveexec_b64 s[10:11], s[6:7]
	s_cbranch_execz .Lmy_rt_sync
	ds_read_b32 v130, v1 offset:512
	v_mov_b32_e32 v131, 0
	v_mov_b32_e32 v132, 0
	s_waitcnt lgkmcnt(0)
	v_lshlrev_b32_e32 v133, 2, v130
	ds_read_b32 v134, v133 offset:128
	ds_read_b32 v135, v133 offset:256
	v_cmp_eq_u32_e32 vcc, 0, v130
	v_cmp_eq_u32_e64 s[98:99], 1, v130
	v_cmp_eq_u32_e64 s[100:101], 2, v130
	s_bcnt1_i32_b64 s0, vcc
	v_mbcnt_lo_u32_b32 v136, vcc_lo, 0
	v_mbcnt_hi_u32_b32 v136, vcc_hi, v136
	v_cndmask_b32_e32 v131, v131, v136, vcc
	v_writelane_b32 v132, s0, 0
	v_cmp_eq_u32_e32 vcc, 3, v130
	s_bcnt1_i32_b64 s0, s[98:99]
	v_mbcnt_lo_u32_b32 v136, s98, 0
	v_mbcnt_hi_u32_b32 v136, s99, v136
	v_cndmask_b32_e64 v131, v131, v136, s[98:99]
	v_writelane_b32 v132, s0, 1
	v_cmp_eq_u32_e64 s[98:99], 4, v130
	s_bcnt1_i32_b64 s0, s[100:101]
	v_mbcnt_lo_u32_b32 v136, s100, 0
	v_mbcnt_hi_u32_b32 v136, s101, v136
	v_cndmask_b32_e64 v131, v131, v136, s[100:101]
	v_writelane_b32 v132, s0, 2
	v_cmp_eq_u32_e64 s[100:101], 5, v130
	s_bcnt1_i32_b64 s0, vcc
	v_mbcnt_lo_u32_b32 v136, vcc_lo, 0
	v_mbcnt_hi_u32_b32 v136, vcc_hi, v136
	v_cndmask_b32_e32 v131, v131, v136, vcc
	v_writelane_b32 v132, s0, 3
	v_cmp_eq_u32_e32 vcc, 6, v130
	s_bcnt1_i32_b64 s0, s[98:99]
	v_mbcnt_lo_u32_b32 v136, s98, 0
	v_mbcnt_hi_u32_b32 v136, s99, v136
	v_cndmask_b32_e64 v131, v131, v136, s[98:99]
	v_writelane_b32 v132, s0, 4
	v_cmp_eq_u32_e64 s[98:99], 7, v130
	s_bcnt1_i32_b64 s0, s[100:101]
	v_mbcnt_lo_u32_b32 v136, s100, 0
	v_mbcnt_hi_u32_b32 v136, s101, v136
	v_cndmask_b32_e64 v131, v131, v136, s[100:101]
	v_writelane_b32 v132, s0, 5
	v_cmp_eq_u32_e64 s[100:101], 8, v130
	s_bcnt1_i32_b64 s0, vcc
	v_mbcnt_lo_u32_b32 v136, vcc_lo, 0
	v_mbcnt_hi_u32_b32 v136, vcc_hi, v136
	v_cndmask_b32_e32 v131, v131, v136, vcc
	v_writelane_b32 v132, s0, 6
	v_cmp_eq_u32_e32 vcc, 9, v130
	s_bcnt1_i32_b64 s0, s[98:99]
	v_mbcnt_lo_u32_b32 v136, s98, 0
	v_mbcnt_hi_u32_b32 v136, s99, v136
	v_cndmask_b32_e64 v131, v131, v136, s[98:99]
	v_writelane_b32 v132, s0, 7
	v_cmp_eq_u32_e64 s[98:99], 10, v130
	s_bcnt1_i32_b64 s0, s[100:101]
	v_mbcnt_lo_u32_b32 v136, s100, 0
	v_mbcnt_hi_u32_b32 v136, s101, v136
	v_cndmask_b32_e64 v131, v131, v136, s[100:101]
	v_writelane_b32 v132, s0, 8
	v_cmp_eq_u32_e64 s[100:101], 11, v130
	s_bcnt1_i32_b64 s0, vcc
	v_mbcnt_lo_u32_b32 v136, vcc_lo, 0
	v_mbcnt_hi_u32_b32 v136, vcc_hi, v136
	v_cndmask_b32_e32 v131, v131, v136, vcc
	v_writelane_b32 v132, s0, 9
	v_cmp_eq_u32_e32 vcc, 12, v130
	s_bcnt1_i32_b64 s0, s[98:99]
	v_mbcnt_lo_u32_b32 v136, s98, 0
	v_mbcnt_hi_u32_b32 v136, s99, v136
	v_cndmask_b32_e64 v131, v131, v136, s[98:99]
	v_writelane_b32 v132, s0, 10
	v_cmp_eq_u32_e64 s[98:99], 13, v130
	s_bcnt1_i32_b64 s0, s[100:101]
	v_mbcnt_lo_u32_b32 v136, s100, 0
	v_mbcnt_hi_u32_b32 v136, s101, v136
	v_cndmask_b32_e64 v131, v131, v136, s[100:101]
	v_writelane_b32 v132, s0, 11
	v_cmp_eq_u32_e64 s[100:101], 14, v130
	s_bcnt1_i32_b64 s0, vcc
	v_mbcnt_lo_u32_b32 v136, vcc_lo, 0
	v_mbcnt_hi_u32_b32 v136, vcc_hi, v136
	v_cndmask_b32_e32 v131, v131, v136, vcc
	v_writelane_b32 v132, s0, 12
	v_cmp_eq_u32_e32 vcc, 15, v130
	s_bcnt1_i32_b64 s0, s[98:99]
	v_mbcnt_lo_u32_b32 v136, s98, 0
	v_mbcnt_hi_u32_b32 v136, s99, v136
	v_cndmask_b32_e64 v131, v131, v136, s[98:99]
	v_writelane_b32 v132, s0, 13
	v_cmp_eq_u32_e64 s[98:99], 16, v130
	s_bcnt1_i32_b64 s0, s[100:101]
	v_mbcnt_lo_u32_b32 v136, s100, 0
	v_mbcnt_hi_u32_b32 v136, s101, v136
	v_cndmask_b32_e64 v131, v131, v136, s[100:101]
	v_writelane_b32 v132, s0, 14
	v_cmp_eq_u32_e64 s[100:101], 17, v130
	s_bcnt1_i32_b64 s0, vcc
	v_mbcnt_lo_u32_b32 v136, vcc_lo, 0
	v_mbcnt_hi_u32_b32 v136, vcc_hi, v136
	v_cndmask_b32_e32 v131, v131, v136, vcc
	v_writelane_b32 v132, s0, 15
	v_cmp_eq_u32_e32 vcc, 18, v130
	s_bcnt1_i32_b64 s0, s[98:99]
	v_mbcnt_lo_u32_b32 v136, s98, 0
	v_mbcnt_hi_u32_b32 v136, s99, v136
	v_cndmask_b32_e64 v131, v131, v136, s[98:99]
	v_writelane_b32 v132, s0, 16
	v_cmp_eq_u32_e64 s[98:99], 19, v130
	s_bcnt1_i32_b64 s0, s[100:101]
	v_mbcnt_lo_u32_b32 v136, s100, 0
	v_mbcnt_hi_u32_b32 v136, s101, v136
	v_cndmask_b32_e64 v131, v131, v136, s[100:101]
	v_writelane_b32 v132, s0, 17
	v_cmp_eq_u32_e64 s[100:101], 20, v130
	s_bcnt1_i32_b64 s0, vcc
	v_mbcnt_lo_u32_b32 v136, vcc_lo, 0
	v_mbcnt_hi_u32_b32 v136, vcc_hi, v136
	v_cndmask_b32_e32 v131, v131, v136, vcc
	v_writelane_b32 v132, s0, 18
	v_cmp_eq_u32_e32 vcc, 21, v130
	s_bcnt1_i32_b64 s0, s[98:99]
	v_mbcnt_lo_u32_b32 v136, s98, 0
	v_mbcnt_hi_u32_b32 v136, s99, v136
	v_cndmask_b32_e64 v131, v131, v136, s[98:99]
	v_writelane_b32 v132, s0, 19
	v_cmp_eq_u32_e64 s[98:99], 22, v130
	s_bcnt1_i32_b64 s0, s[100:101]
	v_mbcnt_lo_u32_b32 v136, s100, 0
	v_mbcnt_hi_u32_b32 v136, s101, v136
	v_cndmask_b32_e64 v131, v131, v136, s[100:101]
	v_writelane_b32 v132, s0, 20
	v_cmp_eq_u32_e64 s[100:101], 23, v130
	s_bcnt1_i32_b64 s0, vcc
	v_mbcnt_lo_u32_b32 v136, vcc_lo, 0
	v_mbcnt_hi_u32_b32 v136, vcc_hi, v136
	v_cndmask_b32_e32 v131, v131, v136, vcc
	v_writelane_b32 v132, s0, 21
	v_cmp_eq_u32_e32 vcc, 24, v130
	s_bcnt1_i32_b64 s0, s[98:99]
	v_mbcnt_lo_u32_b32 v136, s98, 0
	v_mbcnt_hi_u32_b32 v136, s99, v136
	v_cndmask_b32_e64 v131, v131, v136, s[98:99]
	v_writelane_b32 v132, s0, 22
	v_cmp_eq_u32_e64 s[98:99], 25, v130
	s_bcnt1_i32_b64 s0, s[100:101]
	v_mbcnt_lo_u32_b32 v136, s100, 0
	v_mbcnt_hi_u32_b32 v136, s101, v136
	v_cndmask_b32_e64 v131, v131, v136, s[100:101]
	v_writelane_b32 v132, s0, 23
	v_cmp_eq_u32_e64 s[100:101], 26, v130
	s_bcnt1_i32_b64 s0, vcc
	v_mbcnt_lo_u32_b32 v136, vcc_lo, 0
	v_mbcnt_hi_u32_b32 v136, vcc_hi, v136
	v_cndmask_b32_e32 v131, v131, v136, vcc
	v_writelane_b32 v132, s0, 24
	v_cmp_eq_u32_e32 vcc, 27, v130
	s_bcnt1_i32_b64 s0, s[98:99]
	v_mbcnt_lo_u32_b32 v136, s98, 0
	v_mbcnt_hi_u32_b32 v136, s99, v136
	v_cndmask_b32_e64 v131, v131, v136, s[98:99]
	v_writelane_b32 v132, s0, 25
	v_cmp_eq_u32_e64 s[98:99], 28, v130
	s_bcnt1_i32_b64 s0, s[100:101]
	v_mbcnt_lo_u32_b32 v136, s100, 0
	v_mbcnt_hi_u32_b32 v136, s101, v136
	v_cndmask_b32_e64 v131, v131, v136, s[100:101]
	v_writelane_b32 v132, s0, 26
	v_cmp_eq_u32_e64 s[100:101], 29, v130
	s_bcnt1_i32_b64 s0, vcc
	v_mbcnt_lo_u32_b32 v136, vcc_lo, 0
	v_mbcnt_hi_u32_b32 v136, vcc_hi, v136
	v_cndmask_b32_e32 v131, v131, v136, vcc
	v_writelane_b32 v132, s0, 27
	v_cmp_eq_u32_e32 vcc, 30, v130
	s_bcnt1_i32_b64 s0, s[98:99]
	v_mbcnt_lo_u32_b32 v136, s98, 0
	v_mbcnt_hi_u32_b32 v136, s99, v136
	v_cndmask_b32_e64 v131, v131, v136, s[98:99]
	v_writelane_b32 v132, s0, 28
	v_cmp_eq_u32_e64 s[98:99], 31, v130
	s_bcnt1_i32_b64 s0, s[100:101]
	v_mbcnt_lo_u32_b32 v136, s100, 0
	v_mbcnt_hi_u32_b32 v136, s101, v136
	v_cndmask_b32_e64 v131, v131, v136, s[100:101]
	v_writelane_b32 v132, s0, 29
	s_bcnt1_i32_b64 s0, vcc
	v_mbcnt_lo_u32_b32 v136, vcc_lo, 0
	v_mbcnt_hi_u32_b32 v136, vcc_hi, v136
	v_cndmask_b32_e32 v131, v131, v136, vcc
	v_writelane_b32 v132, s0, 30
	s_bcnt1_i32_b64 s0, s[98:99]
	v_mbcnt_lo_u32_b32 v136, s98, 0
	v_mbcnt_hi_u32_b32 v136, s99, v136
	v_cndmask_b32_e64 v131, v131, v136, s[98:99]
	v_writelane_b32 v132, s0, 31
	v_lshrrev_b32_e32 v137, 6, v0
	v_and_b32_e32 v138, 63, v0
	v_lshlrev_b32_e32 v139, 7, v137
	v_lshl_add_u32 v139, v138, 2, v139
	v_cmp_gt_u32_e32 vcc, 32, v138
	s_and_saveexec_b64 s[12:13], vcc
	ds_write_b32 v139, v132 offset:2560
	s_or_b64 exec, exec, s[12:13]
.Lmy_rt_sync:
	s_or_b64 exec, exec, s[10:11]
	s_waitcnt lgkmcnt(0)
	s_barrier
	s_and_saveexec_b64 s[10:11], s[6:7]
	s_cbranch_execz .LBB0_1505
	ds_read_b32 v140, v133 offset:2560
	ds_read_b32 v141, v133 offset:2688
	ds_read_b32 v136, v133 offset:2816
	v_cmp_lt_u32_e32 vcc, 0, v137
	v_cmp_lt_u32_e64 s[98:99], 1, v137
	v_cmp_lt_u32_e64 s[100:101], 2, v137
	v_add3_u32 v131, v131, v134, v135
	s_waitcnt lgkmcnt(0)
	v_cndmask_b32_e32 v140, 0, v140, vcc
	v_cndmask_b32_e64 v141, 0, v141, s[98:99]
	v_cndmask_b32_e64 v136, 0, v136, s[100:101]
	v_add3_u32 v131, v131, v140, v141
	v_add_u32_e32 v131, v131, v136
	ds_write_b32 v1, v131 offset:1536
